# out-proj residual epilogue: residual loads for each pair of row blocks issued 1-2 blocks ahead into rotating free regs v168-199 (4-6 loads in flight, vmcnt recounted 7/6,4/3), on top of graduated wait
# baseline (speedup 1.0000x reference)
; __device__ __forceinline__ unsigned cvt_pk_bf16(float lo, float hi) { unsigned r; asm volatile("v_cvt_pk_bf16_f32 %0, %1, %2" : "=v"(r) : "v"(lo), "v"(hi)); return r; }
;     __device__ __forceinline__ void operator()(const f32x4 (&acc)[2][2][4][2], const Unit& u, int wr, int wc, int fr, int fq) const {
;     ...
;         if (F32BASE) {
; #pragma unroll
;             for (int ai = 0; ai < 2; ++ai)
; #pragma unroll
;                 for (int m = 0; m < 4; ++m) { const size_t roff = (size_t)(row0 + ai * HALF + m * 16) * ldc + col0;
; #pragma unroll
;                     for (int bj = 0; bj < 2; ++bj) { const size_t off = roff + bj * HALF; const f32x4 v0 = acc[ai][bj][m][0] + *(const f32x4*)(basef + off), v1 = acc[ai][bj][m][1] + *(const f32x4*)(basef + off + 4);
;                         u32x4 w; w.x = cvt_pk_bf16(v0[0], v0[1]); w.y = cvt_pk_bf16(v0[2], v0[3]); w.z = cvt_pk_bf16(v1[0], v1[1]); w.w = cvt_pk_bf16(v1[2], v1[3]);
;                         *(u32x4*)(outb + off) = w; }
;                     if (m & 1) asm volatile("" ::: "memory"); }
.LBB0_248:
	v_lshl_add_u32 v148, s68, 8, v150
	v_lshl_or_b32 v146, s24, 8, v152
	v_ashrrev_i32_e32 v149, 31, v148
	v_ashrrev_i32_e32 v147, 31, v146
	v_lshlrev_b64 v[144:145], 11, v[148:149]
	v_lshl_add_u64 v[144:145], v[144:145], 0, v[146:147]
	v_lshl_add_u64 v[164:165], v[144:145], 2, s[36:37]
	global_load_dwordx4 v[156:159], v[164:165], off
	global_load_dwordx4 v[160:163], v[164:165], off offset:16
	global_load_dwordx4 v[176:179], v[164:165], off offset:512
	global_load_dwordx4 v[180:183], v[164:165], off offset:528
	v_lshl_add_u64 v[166:167], v[144:145], 1, s[52:53]
	s_mov_b64 s[24:25], 0x40000
	s_andn2_b64 vcc, exec, s[4:5]
	s_mov_b64 s[4:5], -1
	s_waitcnt vmcnt(2)
	v_pk_add_f32 v[124:125], v[124:125], v[156:157]
	v_pk_add_f32 v[156:157], v[122:123], v[162:163]
	v_pk_add_f32 v[122:123], v[120:121], v[160:161]
	v_pk_add_f32 v[126:127], v[126:127], v[158:159]
	v_cvt_pk_bf16_f32 v120, v124, v125
	s_nop 0
	v_cvt_pk_bf16_f32 v121, v126, v127
	v_cvt_pk_bf16_f32 v122, v122, v123
	v_cvt_pk_bf16_f32 v123, v156, v157
	global_store_dwordx4 v[166:167], v[120:123], off
	s_nop 1
	s_nop 0
	v_or_b32_e32 v156, 16, v148
	v_ashrrev_i32_e32 v157, 31, v156
	v_lshlrev_b64 v[156:157], 11, v[156:157]
	v_lshl_add_u64 v[156:157], v[156:157], 0, v[146:147]
	v_lshl_add_u64 v[158:159], v[156:157], 2, s[36:37]
	global_load_dwordx4 v[184:187], v[158:159], off
	global_load_dwordx4 v[188:191], v[158:159], off offset:16
	global_load_dwordx4 v[192:195], v[158:159], off offset:512
	global_load_dwordx4 v[196:199], v[158:159], off offset:528
	s_waitcnt vmcnt(6)
	v_pk_add_f32 v[116:117], v[116:117], v[176:177]
	s_waitcnt vmcnt(5)
	v_pk_add_f32 v[120:121], v[114:115], v[182:183]
	v_pk_add_f32 v[114:115], v[112:113], v[180:181]
	v_pk_add_f32 v[118:119], v[118:119], v[178:179]
	v_cvt_pk_bf16_f32 v112, v116, v117
	s_nop 0
	v_cvt_pk_bf16_f32 v113, v118, v119
	v_cvt_pk_bf16_f32 v114, v114, v115
	v_cvt_pk_bf16_f32 v115, v120, v121
	global_store_dwordx4 v[166:167], v[112:115], off offset:256
	s_nop 1
	s_nop 0
	v_lshl_add_u64 v[120:121], v[156:157], 1, s[52:53]
	s_waitcnt vmcnt(4)
	v_pk_add_f32 v[108:109], v[108:109], v[184:185]
	s_waitcnt vmcnt(3)
	v_pk_add_f32 v[112:113], v[106:107], v[190:191]
	v_pk_add_f32 v[106:107], v[104:105], v[188:189]
	v_pk_add_f32 v[110:111], v[110:111], v[186:187]
	v_cvt_pk_bf16_f32 v104, v108, v109
	s_nop 0
	v_cvt_pk_bf16_f32 v105, v110, v111
	v_cvt_pk_bf16_f32 v106, v106, v107
	v_cvt_pk_bf16_f32 v107, v112, v113
	global_store_dwordx4 v[120:121], v[104:107], off
	s_nop 1
	s_nop 0
	v_or_b32_e32 v112, 32, v148
	v_ashrrev_i32_e32 v113, 31, v112
	v_lshlrev_b64 v[112:113], 11, v[112:113]
	v_lshl_add_u64 v[112:113], v[112:113], 0, v[146:147]
	v_lshl_add_u64 v[114:115], v[112:113], 2, s[36:37]
	global_load_dwordx4 v[168:171], v[114:115], off
	global_load_dwordx4 v[172:175], v[114:115], off offset:16
	global_load_dwordx4 v[176:179], v[114:115], off offset:512
	global_load_dwordx4 v[180:183], v[114:115], off offset:528
	s_waitcnt vmcnt(7)
	v_pk_add_f32 v[100:101], v[100:101], v[192:193]
	s_waitcnt vmcnt(6)
	v_pk_add_f32 v[104:105], v[98:99], v[198:199]
	v_pk_add_f32 v[98:99], v[96:97], v[196:197]
	v_pk_add_f32 v[102:103], v[102:103], v[194:195]
	v_cvt_pk_bf16_f32 v96, v100, v101
	s_nop 0
	v_cvt_pk_bf16_f32 v97, v102, v103
	v_cvt_pk_bf16_f32 v98, v98, v99
	v_cvt_pk_bf16_f32 v99, v104, v105
	global_store_dwordx4 v[120:121], v[96:99], off offset:256
	s_nop 1
	v_lshl_add_u64 v[104:105], v[112:113], 1, s[52:53]
	s_waitcnt vmcnt(4)
	v_pk_add_f32 v[92:93], v[92:93], v[168:169]
	s_waitcnt vmcnt(3)
	v_pk_add_f32 v[96:97], v[90:91], v[174:175]
	v_pk_add_f32 v[90:91], v[88:89], v[172:173]
	v_pk_add_f32 v[94:95], v[94:95], v[170:171]
	v_cvt_pk_bf16_f32 v88, v92, v93
	s_nop 0
	v_cvt_pk_bf16_f32 v89, v94, v95
	v_cvt_pk_bf16_f32 v90, v90, v91
	v_cvt_pk_bf16_f32 v91, v96, v97
	global_store_dwordx4 v[104:105], v[88:91], off
	s_nop 1
	s_nop 0
	v_or_b32_e32 v96, 48, v148
	v_ashrrev_i32_e32 v97, 31, v96
	v_lshlrev_b64 v[96:97], 11, v[96:97]
	v_lshl_add_u64 v[96:97], v[96:97], 0, v[146:147]
	v_lshl_add_u64 v[98:99], v[96:97], 2, s[36:37]
	global_load_dwordx4 v[184:187], v[98:99], off
	global_load_dwordx4 v[188:191], v[98:99], off offset:16
	global_load_dwordx4 v[192:195], v[98:99], off offset:512
	global_load_dwordx4 v[196:199], v[98:99], off offset:528
	s_waitcnt vmcnt(7)
	v_pk_add_f32 v[84:85], v[84:85], v[176:177]
	s_waitcnt vmcnt(6)
	v_pk_add_f32 v[88:89], v[82:83], v[182:183]
	v_pk_add_f32 v[82:83], v[80:81], v[180:181]
	v_pk_add_f32 v[86:87], v[86:87], v[178:179]
	v_cvt_pk_bf16_f32 v80, v84, v85
	s_nop 0
	v_cvt_pk_bf16_f32 v81, v86, v87
	v_cvt_pk_bf16_f32 v82, v82, v83
	v_cvt_pk_bf16_f32 v83, v88, v89
	global_store_dwordx4 v[104:105], v[80:83], off offset:256
	s_nop 1
	s_nop 0
	v_lshl_add_u64 v[88:89], v[96:97], 1, s[52:53]
	s_waitcnt vmcnt(4)
	v_pk_add_f32 v[76:77], v[76:77], v[184:185]
	s_waitcnt vmcnt(3)
	v_pk_add_f32 v[80:81], v[74:75], v[190:191]
	v_pk_add_f32 v[74:75], v[72:73], v[188:189]
	v_pk_add_f32 v[78:79], v[78:79], v[186:187]
	v_cvt_pk_bf16_f32 v72, v76, v77
	s_nop 0
	v_cvt_pk_bf16_f32 v73, v78, v79
	v_cvt_pk_bf16_f32 v74, v74, v75
	v_cvt_pk_bf16_f32 v75, v80, v81
	global_store_dwordx4 v[88:89], v[72:75], off
	s_nop 1
	s_nop 0
	v_lshl_add_u64 v[80:81], v[144:145], 0, s[24:25]
	v_lshl_add_u64 v[82:83], v[80:81], 2, s[36:37]
	s_mov_b64 s[24:25], 0x48000
	global_load_dwordx4 v[168:171], v[82:83], off
	global_load_dwordx4 v[172:175], v[82:83], off offset:16
	global_load_dwordx4 v[176:179], v[82:83], off offset:512
	global_load_dwordx4 v[180:183], v[82:83], off offset:528
	s_waitcnt vmcnt(7)
; __device__ __forceinline__ unsigned cvt_pk_bf16(float lo, float hi) { unsigned r; asm volatile("v_cvt_pk_bf16_f32 %0, %1, %2" : "=v"(r) : "v"(lo), "v"(hi)); return r; }
;     __device__ __forceinline__ void operator()(const f32x4 (&acc)[2][2][4][2], const Unit& u, int wr, int wc, int fr, int fq) const {
;     ...
;         if (F32BASE) {
; #pragma unroll
;             for (int ai = 0; ai < 2; ++ai)
; #pragma unroll
;                 for (int m = 0; m < 4; ++m) { const size_t roff = (size_t)(row0 + ai * HALF + m * 16) * ldc + col0;
; #pragma unroll
;                     for (int bj = 0; bj < 2; ++bj) { const size_t off = roff + bj * HALF; const f32x4 v0 = acc[ai][bj][m][0] + *(const f32x4*)(basef + off), v1 = acc[ai][bj][m][1] + *(const f32x4*)(basef + off + 4);
;                         u32x4 w; w.x = cvt_pk_bf16(v0[0], v0[1]); w.y = cvt_pk_bf16(v0[2], v0[3]); w.z = cvt_pk_bf16(v1[0], v1[1]); w.w = cvt_pk_bf16(v1[2], v1[3]);
;                         *(u32x4*)(outb + off) = w; }
;                     if (m & 1) asm volatile("" ::: "memory"); }
	v_pk_add_f32 v[68:69], v[68:69], v[192:193]
	s_waitcnt vmcnt(6)
	v_pk_add_f32 v[72:73], v[66:67], v[198:199]
	v_pk_add_f32 v[66:67], v[64:65], v[196:197]
	v_pk_add_f32 v[70:71], v[70:71], v[194:195]
	v_cvt_pk_bf16_f32 v64, v68, v69
	s_nop 0
	v_cvt_pk_bf16_f32 v65, v70, v71
	v_cvt_pk_bf16_f32 v66, v66, v67
	v_cvt_pk_bf16_f32 v67, v72, v73
	global_store_dwordx4 v[88:89], v[64:67], off offset:256
	s_nop 1
	v_lshl_add_u64 v[72:73], v[80:81], 1, s[52:53]
	s_waitcnt vmcnt(4)
	v_pk_add_f32 v[60:61], v[60:61], v[168:169]
	s_waitcnt vmcnt(3)
	v_pk_add_f32 v[64:65], v[58:59], v[174:175]
	v_pk_add_f32 v[58:59], v[56:57], v[172:173]
	v_pk_add_f32 v[62:63], v[62:63], v[170:171]
	v_cvt_pk_bf16_f32 v56, v60, v61
	s_nop 0
	v_cvt_pk_bf16_f32 v57, v62, v63
	v_cvt_pk_bf16_f32 v58, v58, v59
	v_cvt_pk_bf16_f32 v59, v64, v65
	global_store_dwordx4 v[72:73], v[56:59], off
	s_nop 1
	s_nop 0
	v_lshl_add_u64 v[64:65], v[144:145], 0, s[24:25]
	v_lshl_add_u64 v[66:67], v[64:65], 2, s[36:37]
	global_load_dwordx4 v[184:187], v[66:67], off
	global_load_dwordx4 v[188:191], v[66:67], off offset:16
	global_load_dwordx4 v[192:195], v[66:67], off offset:512
	global_load_dwordx4 v[196:199], v[66:67], off offset:528
	s_waitcnt vmcnt(7)
	v_pk_add_f32 v[52:53], v[52:53], v[176:177]
	s_waitcnt vmcnt(6)
	v_pk_add_f32 v[56:57], v[50:51], v[182:183]
	v_pk_add_f32 v[50:51], v[48:49], v[180:181]
	v_pk_add_f32 v[54:55], v[54:55], v[178:179]
	v_cvt_pk_bf16_f32 v48, v52, v53
	s_nop 0
	v_cvt_pk_bf16_f32 v49, v54, v55
	v_cvt_pk_bf16_f32 v50, v50, v51
	v_cvt_pk_bf16_f32 v51, v56, v57
	global_store_dwordx4 v[72:73], v[48:51], off offset:256
	s_nop 1
	s_nop 0
	v_lshl_add_u64 v[56:57], v[64:65], 1, s[52:53]
	s_waitcnt vmcnt(4)
	v_pk_add_f32 v[44:45], v[44:45], v[184:185]
	s_waitcnt vmcnt(3)
	v_pk_add_f32 v[48:49], v[42:43], v[190:191]
	v_pk_add_f32 v[42:43], v[40:41], v[188:189]
	v_pk_add_f32 v[46:47], v[46:47], v[186:187]
	v_cvt_pk_bf16_f32 v40, v44, v45
	s_nop 0
	v_cvt_pk_bf16_f32 v41, v46, v47
	v_cvt_pk_bf16_f32 v42, v42, v43
	v_cvt_pk_bf16_f32 v43, v48, v49
	global_store_dwordx4 v[56:57], v[40:43], off
	s_nop 1
	s_nop 0
	v_lshl_add_u64 v[48:49], v[144:145], 0, s[44:45]
	v_lshl_add_u64 v[50:51], v[48:49], 2, s[36:37]
	global_load_dwordx4 v[168:171], v[50:51], off
	global_load_dwordx4 v[172:175], v[50:51], off offset:16
	global_load_dwordx4 v[176:179], v[50:51], off offset:512
	global_load_dwordx4 v[180:183], v[50:51], off offset:528
	s_waitcnt vmcnt(7)
	v_pk_add_f32 v[36:37], v[36:37], v[192:193]
	s_waitcnt vmcnt(6)
	v_pk_add_f32 v[40:41], v[34:35], v[198:199]
	v_pk_add_f32 v[34:35], v[32:33], v[196:197]
	v_pk_add_f32 v[38:39], v[38:39], v[194:195]
	v_cvt_pk_bf16_f32 v32, v36, v37
	s_nop 0
	v_cvt_pk_bf16_f32 v33, v38, v39
	v_cvt_pk_bf16_f32 v34, v34, v35
	v_cvt_pk_bf16_f32 v35, v40, v41
	global_store_dwordx4 v[56:57], v[32:35], off offset:256
	s_nop 1
	v_lshl_add_u64 v[40:41], v[48:49], 1, s[52:53]
	s_waitcnt vmcnt(4)
	v_pk_add_f32 v[28:29], v[28:29], v[168:169]
	s_waitcnt vmcnt(3)
	v_pk_add_f32 v[32:33], v[26:27], v[174:175]
	v_pk_add_f32 v[26:27], v[24:25], v[172:173]
	v_pk_add_f32 v[30:31], v[30:31], v[170:171]
	v_cvt_pk_bf16_f32 v24, v28, v29
	s_nop 0
	v_cvt_pk_bf16_f32 v25, v30, v31
	v_cvt_pk_bf16_f32 v26, v26, v27
	v_cvt_pk_bf16_f32 v27, v32, v33
	global_store_dwordx4 v[40:41], v[24:27], off
	s_nop 1
	s_nop 0
	v_lshl_add_u64 v[32:33], v[144:145], 0, s[48:49]
	v_lshl_add_u64 v[34:35], v[32:33], 2, s[36:37]
	global_load_dwordx4 v[184:187], v[34:35], off
	global_load_dwordx4 v[188:191], v[34:35], off offset:16
	global_load_dwordx4 v[192:195], v[34:35], off offset:512
	global_load_dwordx4 v[196:199], v[34:35], off offset:528
	s_waitcnt vmcnt(7)
	v_pk_add_f32 v[20:21], v[20:21], v[176:177]
	s_waitcnt vmcnt(6)
	v_pk_add_f32 v[24:25], v[18:19], v[182:183]
	v_pk_add_f32 v[18:19], v[16:17], v[180:181]
	v_pk_add_f32 v[22:23], v[22:23], v[178:179]
	v_cvt_pk_bf16_f32 v16, v20, v21
	s_nop 0
	v_cvt_pk_bf16_f32 v17, v22, v23
	v_cvt_pk_bf16_f32 v18, v18, v19
	v_cvt_pk_bf16_f32 v19, v24, v25
	global_store_dwordx4 v[40:41], v[16:19], off offset:256
	s_nop 1
	s_nop 0
	v_lshl_add_u64 v[24:25], v[32:33], 1, s[52:53]
	s_waitcnt vmcnt(4)
	v_pk_add_f32 v[12:13], v[12:13], v[184:185]
	s_waitcnt vmcnt(3)
	v_pk_add_f32 v[16:17], v[10:11], v[190:191]
	v_pk_add_f32 v[10:11], v[8:9], v[188:189]
	v_pk_add_f32 v[14:15], v[14:15], v[186:187]
	v_cvt_pk_bf16_f32 v8, v12, v13
	s_nop 0
	v_cvt_pk_bf16_f32 v9, v14, v15
	v_cvt_pk_bf16_f32 v10, v10, v11
	v_cvt_pk_bf16_f32 v11, v16, v17
	global_store_dwordx4 v[24:25], v[8:11], off
	s_nop 1
	s_nop 0
	s_waitcnt vmcnt(3)
	v_pk_add_f32 v[4:5], v[4:5], v[192:193]
	s_waitcnt vmcnt(2)
	v_pk_add_f32 v[8:9], v[2:3], v[198:199]
	v_pk_add_f32 v[2:3], v[0:1], v[196:197]
	v_pk_add_f32 v[6:7], v[6:7], v[194:195]
	v_cvt_pk_bf16_f32 v0, v4, v5
	s_nop 0
	v_cvt_pk_bf16_f32 v1, v6, v7
	v_cvt_pk_bf16_f32 v2, v2, v3
	v_cvt_pk_bf16_f32 v3, v8, v9
	global_store_dwordx4 v[24:25], v[0:3], off offset:256
	s_cbranch_vccnz .LBB0_237
	s_andn2_b64 vcc, exec, s[6:7]
	s_cbranch_vccnz .LBB0_236
	s_barrier
	s_branch .LBB0_236
